# v5 + NA: all 26 rel-pos-bias LDS reads of a tile batched before the mask section (one wait instead of 32 serial round trips)
# speedup vs baseline: 1.0402x; 1.0045x over previous
.LBB0_1557:
	s_or_b64 exec, exec, s[6:7]
	v_add_u32_e32 v207, s14, v122
	ds_read_b32 v208, v207 offset:37792
	ds_read_b32 v209, v207 offset:37800
	ds_read_b32 v210, v207 offset:37796
	ds_read_b32 v211, v207 offset:37804
	ds_read_b32 v212, v207 offset:37856
	ds_read_b32 v213, v207 offset:37864
	ds_read_b32 v214, v207 offset:37860
	ds_read_b32 v215, v207 offset:37868
	ds_read_b32 v216, v207 offset:37920
	ds_read_b32 v217, v207 offset:37928
	ds_read_b32 v218, v207 offset:37924
	ds_read_b32 v219, v207 offset:37932
	ds_read_b32 v220, v207 offset:37984
	ds_read_b32 v221, v207 offset:37992
	ds_read_b32 v222, v207 offset:37988
	ds_read_b32 v223, v207 offset:37996
	ds_read_b32 v224, v207 offset:37668
	ds_read_b32 v225, v207 offset:37676
	ds_read_b32 v226, v207 offset:37732
	ds_read_b32 v227, v207 offset:37740
	ds_read_b32 v228, v207 offset:37672
	ds_read_b32 v229, v207 offset:37680
	ds_read_b32 v230, v207 offset:37736
	ds_read_b32 v231, v207 offset:37744
	ds_read_b32 v232, v207 offset:37808
	ds_read_b32 v233, v207 offset:37872
	s_add_i32 s6, s15, -9
	v_mov_b32_e32 v133, s6
	v_cndmask_b32_e32 v133, v127, v133, vcc
	v_cmp_gt_u32_e64 s[58:59], 64, v133
	v_cmp_ge_i32_e64 s[60:61], v127, v117
	s_and_b64 s[96:97], s[58:59], s[66:67]
	v_cmp_lt_i32_e64 s[56:57], v127, v118
	s_and_b64 s[6:7], s[96:97], s[60:61]
	v_cndmask_b32_e64 v133, 0, 1, s[4:5]
	v_cmp_ne_u32_e64 s[54:55], 1, v133
	s_andn2_b64 vcc, exec, s[4:5]
	s_and_b64 s[4:5], s[6:7], s[56:57]
	s_cbranch_vccnz .LBB0_1565
	v_readlane_b32 s6, v254, 55
	v_readlane_b32 s7, v254, 56
	s_and_b64 s[62:63], s[4:5], s[6:7]
	v_mov_b32_e32 v133, 0xf149f2ca
	s_and_saveexec_b64 s[6:7], s[62:63]
	s_cbranch_execz .LBB0_1560
	s_waitcnt lgkmcnt(0)
	v_add_f32_e32 v133, v92, v208

.LBB0_1562:
	v_readlane_b32 s6, v254, 59
	v_readlane_b32 s7, v254, 60
	s_and_b64 s[62:63], s[4:5], s[6:7]
	v_mov_b32_e32 v133, 0xf149f2ca
	s_and_saveexec_b64 s[6:7], s[62:63]
	s_cbranch_execz .LBB0_1564
	s_waitcnt lgkmcnt(0)
	v_add_f32_e32 v133, v94, v209

.LBB0_1566:
	v_readlane_b32 s6, v254, 57
	v_readlane_b32 s7, v254, 58
	s_and_b64 s[62:63], s[4:5], s[6:7]
	v_mov_b32_e32 v133, 0xf149f2ca
	s_and_saveexec_b64 s[6:7], s[62:63]
	s_cbranch_execz .LBB0_1568
	s_waitcnt lgkmcnt(0)
	v_add_f32_e32 v133, v93, v210

.LBB0_1570:
	v_readlane_b32 s6, v254, 61
	v_readlane_b32 s7, v254, 62
	s_and_b64 s[6:7], s[4:5], s[6:7]
	v_mov_b32_e32 v133, 0xf149f2ca
	s_and_saveexec_b64 s[4:5], s[6:7]
	s_cbranch_execz .LBB0_1572
	s_waitcnt lgkmcnt(0)
	v_add_f32_e32 v133, v95, v211

.LBB0_1573:
	v_readlane_b32 s4, v254, 63
	v_readlane_b32 s5, v255, 0
	s_and_b64 s[62:63], s[58:59], s[4:5]
	s_and_b64 s[4:5], s[62:63], s[60:61]
	s_and_b64 vcc, exec, s[54:55]
	s_and_b64 s[4:5], s[4:5], s[56:57]
	s_cbranch_vccnz .LBB0_1581
	v_readlane_b32 s6, v255, 1
	v_readlane_b32 s7, v255, 2
	v_readlane_b32 s16, v255, 3
	s_and_b64 s[6:7], s[4:5], s[6:7]
	v_readlane_b32 s17, v255, 4
	s_and_b64 vcc, s[6:7], s[16:17]
	v_mov_b32_e32 v133, 0xf149f2ca
	s_and_saveexec_b64 s[6:7], vcc
	s_cbranch_execz .LBB0_1576
	s_waitcnt lgkmcnt(0)
	v_add_f32_e32 v133, v88, v212

.LBB0_1578:
	s_and_b64 s[6:7], s[4:5], s[20:21]
	s_and_b64 vcc, s[6:7], s[22:23]
	v_mov_b32_e32 v133, 0xf149f2ca
	s_and_saveexec_b64 s[6:7], vcc
	s_cbranch_execz .LBB0_1580
	s_waitcnt lgkmcnt(0)
	v_add_f32_e32 v133, v90, v213

.LBB0_1582:
	v_readlane_b32 s6, v255, 5
	v_readlane_b32 s7, v255, 6
	s_and_b64 s[6:7], s[4:5], s[6:7]
	s_and_b64 vcc, s[6:7], s[18:19]
	v_mov_b32_e32 v133, 0xf149f2ca
	s_and_saveexec_b64 s[6:7], vcc
	s_cbranch_execz .LBB0_1584
	s_waitcnt lgkmcnt(0)
	v_add_f32_e32 v133, v89, v214

.LBB0_1586:
	s_and_b64 s[4:5], s[4:5], s[24:25]
	s_and_b64 s[6:7], s[4:5], s[26:27]
	v_mov_b32_e32 v133, 0xf149f2ca
	s_and_saveexec_b64 s[4:5], s[6:7]
	s_cbranch_execz .LBB0_1588
	s_waitcnt lgkmcnt(0)
	v_add_f32_e32 v133, v91, v215

.LBB0_1589:
	s_and_b64 s[4:5], s[58:59], s[2:3]
	s_and_b64 s[6:7], s[4:5], s[60:61]
	s_and_b64 vcc, exec, s[54:55]
	s_and_b64 s[6:7], s[6:7], s[56:57]
	s_cbranch_vccnz .LBB0_1597
	s_and_b64 vcc, s[6:7], s[28:29]
	s_and_b64 s[16:17], vcc, s[30:31]
	v_mov_b32_e32 v133, 0xf149f2ca
	s_and_saveexec_b64 vcc, s[16:17]
	s_cbranch_execz .LBB0_1592
	s_waitcnt lgkmcnt(0)
	v_add_f32_e32 v133, v68, v216

.LBB0_1594:
	s_and_b64 s[16:17], s[6:7], s[38:39]
	s_and_b64 s[16:17], s[16:17], s[8:9]
	v_mov_b32_e32 v133, 0xf149f2ca
	s_and_saveexec_b64 vcc, s[16:17]
	s_cbranch_execz .LBB0_1596
	s_waitcnt lgkmcnt(0)
	v_add_f32_e32 v133, v70, v217

.LBB0_1598:
	s_and_b64 s[16:17], s[6:7], s[34:35]
	s_and_b64 s[16:17], s[16:17], s[36:37]
	v_mov_b32_e32 v133, 0xf149f2ca
	s_and_saveexec_b64 vcc, s[16:17]
	s_cbranch_execz .LBB0_1600
	s_waitcnt lgkmcnt(0)
	v_add_f32_e32 v133, v69, v218

.LBB0_1602:
	s_and_b64 s[6:7], s[6:7], s[10:11]
	s_and_b64 s[16:17], s[6:7], s[0:1]
	v_mov_b32_e32 v133, 0xf149f2ca
	s_and_saveexec_b64 s[6:7], s[16:17]
	s_cbranch_execz .LBB0_1604
	s_waitcnt lgkmcnt(0)
	v_add_f32_e32 v133, v71, v219

.LBB0_1605:
	s_and_b64 s[6:7], s[58:59], s[68:69]
	s_and_b64 s[16:17], s[6:7], s[60:61]
	s_and_b64 vcc, exec, s[54:55]
	s_and_b64 s[56:57], s[16:17], s[56:57]
	s_cbranch_vccnz .LBB0_1613
	s_and_b64 s[16:17], s[56:57], s[12:13]
	v_mov_b32_e32 v133, 0xf149f2ca
	s_and_saveexec_b64 s[58:59], s[16:17]
	s_cbranch_execz .LBB0_1608
	s_waitcnt lgkmcnt(0)
	v_add_f32_e32 v133, v64, v220

.LBB0_1610:
	s_and_b64 s[16:17], s[56:57], s[50:51]
	v_mov_b32_e32 v133, 0xf149f2ca
	s_and_saveexec_b64 s[58:59], s[16:17]
	s_cbranch_execz .LBB0_1612
	s_waitcnt lgkmcnt(0)
	v_add_f32_e32 v133, v66, v221

.LBB0_1614:
	s_and_b64 s[16:17], s[56:57], s[48:49]
	v_mov_b32_e32 v133, 0xf149f2ca
	s_and_saveexec_b64 s[58:59], s[16:17]
	s_cbranch_execz .LBB0_1616
	s_waitcnt lgkmcnt(0)
	v_add_f32_e32 v133, v65, v222

.LBB0_1618:
	s_and_b64 s[16:17], s[56:57], s[52:53]
	v_mov_b32_e32 v133, 0xf149f2ca
	s_and_saveexec_b64 s[56:57], s[16:17]
	s_cbranch_execz .LBB0_1620
	s_waitcnt lgkmcnt(0)
	v_add_f32_e32 v133, v67, v223

.LBB0_1621:
	s_mov_b32 s16, 0xf149f2ca
	v_max3_f32 v133, v92, s16, v93
	v_max3_f32 v133, v133, v94, v95
	v_max3_f32 v133, v133, v88, v89
	v_max3_f32 v133, v133, v90, v91
	v_max3_f32 v133, v133, v68, v69
	v_max3_f32 v133, v133, v70, v71
	v_max3_f32 v133, v133, v64, v65
	v_max3_f32 v133, v133, v66, v67
	ds_bpermute_b32 v134, v106, v133
	v_cmp_ge_i32_e64 s[58:59], v127, v119
	v_cmp_lt_i32_e64 s[56:57], v127, v120
	s_and_b64 s[16:17], s[96:97], s[58:59]
	s_and_b64 vcc, exec, s[54:55]
	s_waitcnt lgkmcnt(0)
	v_max_f32_e32 v134, v134, v134
	v_max_f32_e32 v133, v133, v134
	ds_bpermute_b32 v134, v105, v133
	s_and_b64 s[60:61], s[16:17], s[56:57]
	s_cbranch_vccnz .LBB0_1653
	v_readlane_b32 s16, v254, 55
	v_readlane_b32 s17, v254, 56
	s_and_b64 s[16:17], s[60:61], s[16:17]
	v_mov_b32_e32 v127, 0xf149f2ca
	s_and_saveexec_b64 s[96:97], s[16:17]
	s_cbranch_execz .LBB0_1624
	s_waitcnt lgkmcnt(0)
	v_add_f32_e32 v127, v84, v224

.LBB0_1626:
	v_readlane_b32 s16, v254, 59
	v_readlane_b32 s17, v254, 60
	s_and_b64 s[16:17], s[60:61], s[16:17]
	v_mov_b32_e32 v127, 0xf149f2ca
	s_and_saveexec_b64 s[96:97], s[16:17]
	s_cbranch_execz .LBB0_1628
	s_waitcnt lgkmcnt(0)
	v_add_f32_e32 v127, v86, v225

.LBB0_1630:
	v_readlane_b32 s16, v255, 1
	v_readlane_b32 s17, v255, 2
	v_readlane_b32 s62, v255, 3
	s_and_b64 s[16:17], s[60:61], s[16:17]
	v_readlane_b32 s63, v255, 4
	s_and_b64 s[16:17], s[16:17], s[62:63]
	v_mov_b32_e32 v127, 0xf149f2ca
	s_and_saveexec_b64 s[62:63], s[16:17]
	s_cbranch_execz .LBB0_1632
	s_waitcnt lgkmcnt(0)
	v_add_f32_e32 v127, v80, v226

.LBB0_1634:
	s_and_b64 s[16:17], s[60:61], s[20:21]
	s_and_b64 s[16:17], s[16:17], s[22:23]
	v_mov_b32_e32 v127, 0xf149f2ca
	s_and_saveexec_b64 s[62:63], s[16:17]
	s_cbranch_execz .LBB0_1636
	s_waitcnt lgkmcnt(0)
	v_add_f32_e32 v127, v82, v227

.LBB0_1638:
	s_and_b64 s[16:17], s[4:5], s[28:29]
	s_and_b64 s[16:17], s[16:17], s[30:31]
	v_mov_b32_e32 v127, 0xf149f2ca
	s_and_saveexec_b64 s[60:61], s[16:17]
	s_cbranch_execz .LBB0_1640
	s_waitcnt lgkmcnt(0)
	v_add_f32_e32 v127, v76, v210

.LBB0_1642:
	s_and_b64 s[16:17], s[4:5], s[38:39]
	s_and_b64 s[16:17], s[16:17], s[8:9]
	v_mov_b32_e32 v127, 0xf149f2ca
	s_and_saveexec_b64 s[60:61], s[16:17]
	s_cbranch_execz .LBB0_1644
	s_waitcnt lgkmcnt(0)
	v_add_f32_e32 v127, v78, v211

.LBB0_1646:
	s_and_b64 s[16:17], s[6:7], s[12:13]
	v_mov_b32_e32 v127, 0xf149f2ca
	s_and_saveexec_b64 s[4:5], s[16:17]
	s_cbranch_execz .LBB0_1648
	s_waitcnt lgkmcnt(0)
	v_add_f32_e32 v127, v72, v214

.LBB0_1650:
	s_and_b64 s[16:17], s[6:7], s[50:51]
	v_mov_b32_e32 v127, 0xf149f2ca
	s_and_saveexec_b64 s[4:5], s[16:17]
	s_cbranch_execz .LBB0_1652
	s_waitcnt lgkmcnt(0)
	v_add_f32_e32 v127, v74, v215

.LBB0_1654:
	v_readlane_b32 s16, v254, 57
	v_readlane_b32 s17, v254, 58
	s_and_b64 s[16:17], s[60:61], s[16:17]
	v_mov_b32_e32 v127, 0xf149f2ca
	s_and_saveexec_b64 s[96:97], s[16:17]
	s_cbranch_execz .LBB0_1656
	s_waitcnt lgkmcnt(0)
	v_add_f32_e32 v127, v85, v228

.LBB0_1658:
	v_readlane_b32 s16, v254, 61
	v_readlane_b32 s17, v254, 62
	s_and_b64 s[16:17], s[60:61], s[16:17]
	v_mov_b32_e32 v127, 0xf149f2ca
	s_and_saveexec_b64 s[60:61], s[16:17]
	s_cbranch_execz .LBB0_1660
	s_waitcnt lgkmcnt(0)
	v_add_f32_e32 v127, v87, v229

.LBB0_1662:
	v_readlane_b32 s16, v255, 5
	v_readlane_b32 s17, v255, 6
	s_and_b64 s[16:17], s[60:61], s[16:17]
	s_and_b64 s[16:17], s[16:17], s[18:19]
	v_mov_b32_e32 v127, 0xf149f2ca
	s_and_saveexec_b64 s[62:63], s[16:17]
	s_cbranch_execz .LBB0_1664
	s_waitcnt lgkmcnt(0)
	v_add_f32_e32 v127, v81, v230

.LBB0_1666:
	s_and_b64 s[16:17], s[60:61], s[24:25]
	s_and_b64 s[16:17], s[16:17], s[26:27]
	v_mov_b32_e32 v127, 0xf149f2ca
	s_and_saveexec_b64 s[60:61], s[16:17]
	s_cbranch_execz .LBB0_1668
	s_waitcnt lgkmcnt(0)
	v_add_f32_e32 v127, v83, v231

.LBB0_1670:
	s_and_b64 s[16:17], s[4:5], s[34:35]
	s_and_b64 s[16:17], s[16:17], s[36:37]
	v_mov_b32_e32 v127, 0xf149f2ca
	s_and_saveexec_b64 s[60:61], s[16:17]
	s_cbranch_execz .LBB0_1672
	s_waitcnt lgkmcnt(0)
	v_add_f32_e32 v127, v77, v209

.LBB0_1674:
	s_and_b64 s[4:5], s[4:5], s[10:11]
	s_and_b64 s[16:17], s[4:5], s[0:1]
	v_mov_b32_e32 v127, 0xf149f2ca
	s_and_saveexec_b64 s[4:5], s[16:17]
	s_cbranch_execz .LBB0_1676
	s_waitcnt lgkmcnt(0)
	v_add_f32_e32 v127, v79, v232

.LBB0_1678:
	s_and_b64 s[16:17], s[6:7], s[48:49]
	v_mov_b32_e32 v127, 0xf149f2ca
	s_and_saveexec_b64 s[4:5], s[16:17]
	s_cbranch_execz .LBB0_1680
	s_waitcnt lgkmcnt(0)
	v_add_f32_e32 v127, v73, v213

.LBB0_1682:
	s_and_b64 s[6:7], s[6:7], s[52:53]
	v_mov_b32_e32 v127, 0xf149f2ca
	s_and_saveexec_b64 s[4:5], s[6:7]
	s_cbranch_execz .LBB0_1684
	s_waitcnt lgkmcnt(0)
	v_add_f32_e32 v127, v75, v233
